# attention far tiles: QK^T accumulators start from C=0 and the constant bias c is folded into the softmax offset (no 32-register init per step)
# speedup vs baseline: 1.0160x; 1.0024x over previous
; #define LAS __attribute__((address_space(3)))
; __device__ __forceinline__ void qkt(f32x16& p0, f32x16& p1, const char* Ks, const bf16x8* qr, int r32, int hi, const LAS float* tab, int rel0, int farmode) {
;   if (farmode != 0) { const float c = tab[farmode < 0 ? 0 : 384];
; #pragma unroll
;     for (int r = 0; r < 16; ++r) { p0[r] = c; p1[r] = c; }
;   } else {
;     const LAS float* tb = tab + (rel0 + 192 + 4 * hi);
; #pragma unroll
;     for (int r = 0; r < 16; ++r) { p0[r] = tb[(r & 3) + 8 * (r >> 2)]; p1[r] = tb[32 + (r & 3) + 8 * (r >> 2)]; }
.LBB0_113:
	s_setprio 2
	v_add_u32_e32 v160, s8, v226
	ds_read_b64_tr_b16 v[144:145], v160 offset:0
	ds_read_b64_tr_b16 v[146:147], v160 offset:0x800
	ds_read_b64_tr_b16 v[148:149], v160 offset:0x1000
	ds_read_b64_tr_b16 v[150:151], v160 offset:0x1800
	ds_read_b64_tr_b16 v[152:153], v160 offset:0x2000
	ds_read_b64_tr_b16 v[154:155], v160 offset:0x2800
	ds_read_b64_tr_b16 v[156:157], v160 offset:0x3000
	ds_read_b64_tr_b16 v[158:159], v160 offset:0x3800
	ds_read_b64_tr_b16 v[194:195], v160 offset:0x200
	ds_read_b64_tr_b16 v[196:197], v160 offset:0xa00
	ds_read_b64_tr_b16 v[198:199], v160 offset:0x1200
	ds_read_b64_tr_b16 v[200:201], v160 offset:0x1a00
	ds_read_b64_tr_b16 v[202:203], v160 offset:0x2200
	ds_read_b64_tr_b16 v[204:205], v160 offset:0x2a00
	ds_read_b64_tr_b16 v[206:207], v160 offset:0x3200
	ds_read_b64_tr_b16 v[208:209], v160 offset:0x3a00
	s_waitcnt lgkmcnt(8)
	s_nop 0
	v_mfma_f32_32x32x16_bf16 v[96:111], v[128:131], v[144:147], v[96:111]
	v_mfma_f32_32x32x16_bf16 v[96:111], v[132:135], v[148:151], v[96:111]
	v_mfma_f32_32x32x16_bf16 v[96:111], v[136:139], v[152:155], v[96:111]
	v_mfma_f32_32x32x16_bf16 v[96:111], v[140:143], v[156:159], v[96:111]
	ds_read_b64_tr_b16 v[144:145], v160 offset:0x400
	ds_read_b64_tr_b16 v[146:147], v160 offset:0xc00
	ds_read_b64_tr_b16 v[148:149], v160 offset:0x1400
	ds_read_b64_tr_b16 v[150:151], v160 offset:0x1c00
	ds_read_b64_tr_b16 v[152:153], v160 offset:0x2400
	ds_read_b64_tr_b16 v[154:155], v160 offset:0x2c00
	ds_read_b64_tr_b16 v[156:157], v160 offset:0x3400
	ds_read_b64_tr_b16 v[158:159], v160 offset:0x3c00
	s_waitcnt lgkmcnt(8)
	v_mfma_f32_32x32x16_bf16 v[112:127], v[128:131], v[194:197], v[112:127]
	v_mfma_f32_32x32x16_bf16 v[112:127], v[132:135], v[198:201], v[112:127]
	v_mfma_f32_32x32x16_bf16 v[112:127], v[136:139], v[202:205], v[112:127]
	v_mfma_f32_32x32x16_bf16 v[112:127], v[140:143], v[206:209], v[112:127]
	ds_read_b64_tr_b16 v[194:195], v160 offset:0x600
	ds_read_b64_tr_b16 v[196:197], v160 offset:0xe00
	ds_read_b64_tr_b16 v[198:199], v160 offset:0x1600
	ds_read_b64_tr_b16 v[200:201], v160 offset:0x1e00
	ds_read_b64_tr_b16 v[202:203], v160 offset:0x2600
	ds_read_b64_tr_b16 v[204:205], v160 offset:0x2e00
	ds_read_b64_tr_b16 v[206:207], v160 offset:0x3600
	ds_read_b64_tr_b16 v[208:209], v160 offset:0x3e00
	s_waitcnt lgkmcnt(8)
	v_mfma_f32_32x32x16_bf16 v[80:95], v[128:131], v[144:147], v[80:95]
	v_mfma_f32_32x32x16_bf16 v[80:95], v[132:135], v[148:151], v[80:95]
	v_mfma_f32_32x32x16_bf16 v[80:95], v[136:139], v[152:155], v[80:95]
	v_mfma_f32_32x32x16_bf16 v[80:95], v[140:143], v[156:159], v[80:95]
	ds_read_b64_tr_b16 v[144:145], v160 offset:0x4000
	ds_read_b64_tr_b16 v[146:147], v160 offset:0x4800
	ds_read_b64_tr_b16 v[148:149], v160 offset:0x5000
	ds_read_b64_tr_b16 v[150:151], v160 offset:0x5800
	ds_read_b64_tr_b16 v[152:153], v160 offset:0x6000
	ds_read_b64_tr_b16 v[154:155], v160 offset:0x6800
	ds_read_b64_tr_b16 v[156:157], v160 offset:0x7000
	ds_read_b64_tr_b16 v[158:159], v160 offset:0x7800
	s_waitcnt lgkmcnt(8)
	v_mfma_f32_32x32x16_bf16 v[64:79], v[128:131], v[194:197], v[64:79]
	v_mfma_f32_32x32x16_bf16 v[64:79], v[132:135], v[198:201], v[64:79]
	v_mfma_f32_32x32x16_bf16 v[64:79], v[136:139], v[202:205], v[64:79]
	v_mfma_f32_32x32x16_bf16 v[64:79], v[140:143], v[206:209], v[64:79]
	ds_read_b64_tr_b16 v[194:195], v160 offset:0x4200
	ds_read_b64_tr_b16 v[196:197], v160 offset:0x4a00
	ds_read_b64_tr_b16 v[198:199], v160 offset:0x5200
	ds_read_b64_tr_b16 v[200:201], v160 offset:0x5a00
	ds_read_b64_tr_b16 v[202:203], v160 offset:0x6200
	ds_read_b64_tr_b16 v[204:205], v160 offset:0x6a00
	ds_read_b64_tr_b16 v[206:207], v160 offset:0x7200
	ds_read_b64_tr_b16 v[208:209], v160 offset:0x7a00
	s_waitcnt lgkmcnt(8)
	v_mfma_f32_32x32x16_bf16 v[48:63], v[128:131], v[144:147], v[48:63]
	v_mfma_f32_32x32x16_bf16 v[48:63], v[132:135], v[148:151], v[48:63]
	v_mfma_f32_32x32x16_bf16 v[48:63], v[136:139], v[152:155], v[48:63]
	v_mfma_f32_32x32x16_bf16 v[48:63], v[140:143], v[156:159], v[48:63]
	ds_read_b64_tr_b16 v[144:145], v160 offset:0x4400
	ds_read_b64_tr_b16 v[146:147], v160 offset:0x4c00
	ds_read_b64_tr_b16 v[148:149], v160 offset:0x5400
	ds_read_b64_tr_b16 v[150:151], v160 offset:0x5c00
	ds_read_b64_tr_b16 v[152:153], v160 offset:0x6400
	ds_read_b64_tr_b16 v[154:155], v160 offset:0x6c00
	ds_read_b64_tr_b16 v[156:157], v160 offset:0x7400
	ds_read_b64_tr_b16 v[158:159], v160 offset:0x7c00
	s_waitcnt lgkmcnt(8)
	v_mfma_f32_32x32x16_bf16 v[32:47], v[128:131], v[194:197], v[32:47]
	v_mfma_f32_32x32x16_bf16 v[32:47], v[132:135], v[198:201], v[32:47]
	v_mfma_f32_32x32x16_bf16 v[32:47], v[136:139], v[202:205], v[32:47]
	v_mfma_f32_32x32x16_bf16 v[32:47], v[140:143], v[206:209], v[32:47]
	ds_read_b64_tr_b16 v[194:195], v160 offset:0x4600
	ds_read_b64_tr_b16 v[196:197], v160 offset:0x4e00
	ds_read_b64_tr_b16 v[198:199], v160 offset:0x5600
	ds_read_b64_tr_b16 v[200:201], v160 offset:0x5e00
	ds_read_b64_tr_b16 v[202:203], v160 offset:0x6600
	ds_read_b64_tr_b16 v[204:205], v160 offset:0x6e00
	ds_read_b64_tr_b16 v[206:207], v160 offset:0x7600
	ds_read_b64_tr_b16 v[208:209], v160 offset:0x7e00
	s_waitcnt lgkmcnt(8)
	v_mfma_f32_32x32x16_bf16 v[16:31], v[128:131], v[144:147], v[16:31]
	v_mfma_f32_32x32x16_bf16 v[16:31], v[132:135], v[148:151], v[16:31]
	v_mfma_f32_32x32x16_bf16 v[16:31], v[136:139], v[152:155], v[16:31]
	v_mfma_f32_32x32x16_bf16 v[16:31], v[140:143], v[156:159], v[16:31]
	s_waitcnt lgkmcnt(0)
	v_mfma_f32_32x32x16_bf16 v[0:15], v[128:131], v[194:197], v[0:15]
	v_mfma_f32_32x32x16_bf16 v[0:15], v[132:135], v[198:201], v[0:15]
	v_mfma_f32_32x32x16_bf16 v[0:15], v[136:139], v[202:205], v[0:15]
	v_mfma_f32_32x32x16_bf16 v[0:15], v[140:143], v[206:209], v[0:15]
	s_setprio 1
	s_cmpk_lt_u32 s77, 0x113
	s_cbranch_scc1 .LBB0_115
	s_add_i32 s8, s77, 0xffffff67
	s_cmpk_gt_i32 s8, 0xff66
	s_cselect_b32 s8, 0x600, 0
	s_add_i32 s8, s8, 0
	s_add_i32 s8, s8, 0x24800
	v_mov_b32_e32 v128, s8
	ds_read_b32 v160, v128
	s_mov_b32 s32, 1
	s_waitcnt lgkmcnt(0)
	v_mul_f32_e32 v128, 0x3fb8aa3b, v160
	v_readfirstlane_b32 s99, v160
	v_readfirstlane_b32 s98, v128
	s_branch .LBB0_118
; #define LAS __attribute__((address_space(3)))
; __device__ __forceinline__ void partialSM(f32x16& p0, f32x16& p1, float& m_reg, float& mn, float& alpha) {
;   constexpr float C = LOG2E;
;   float pmax = p0[0];
; #pragma unroll
;   for (int r = 1; r < 16; ++r) pmax = fmaxf(pmax, p0[r]);
; #pragma unroll
;   for (int r = 0; r < 16; ++r) pmax = fmaxf(pmax, p1[r]);
;   { auto rr = __builtin_amdgcn_permlane32_swap(__float_as_uint(pmax), __float_as_uint(pmax), false, false);
;     pmax = fmaxf(__uint_as_float(rr[0]), __uint_as_float(rr[1])); }
;   if (__builtin_expect(__all(pmax - m_reg <= THR), 1)) { mn = m_reg; alpha = 1.f; }
;   else { mn = fmaxf(m_reg, pmax); alpha = __builtin_amdgcn_exp2f((m_reg - mn) * C); m_reg = mn; }
; __device__ __forceinline__ void qkt(f32x16& p0, f32x16& p1, const char* Ks, const bf16x8* qr, int r32, int hi, const LAS float* tab, int rel0, int farmode) {
;   if (farmode != 0) { const float c = tab[farmode < 0 ? 0 : 384];
; #pragma unroll
;     for (int r = 0; r < 16; ++r) { p0[r] = c; p1[r] = c; }
;   } else {
;     const LAS float* tb = tab + (rel0 + 192 + 4 * hi);
; #pragma unroll
;     for (int r = 0; r < 16; ++r) { p0[r] = tb[(r & 3) + 8 * (r >> 2)]; p1[r] = tb[32 + (r & 3) + 8 * (r >> 2)]; }
;   }
; #pragma unroll
;   for (int d0 = 0; d0 < 8; ++d0) { int cb = (d0 * 16 + hi * 8) * 2;
;     bf16x8 b0 = *reinterpret_cast<const bf16x8*>(Ks + KSWZ(r32, cb));
;     bf16x8 b1 = *reinterpret_cast<const bf16x8*>(Ks + KSWZ(32 + r32, cb));
;     p0 = __builtin_amdgcn_mfma_f32_32x32x16_bf16(b0, qr[d0], p0, 0, 0, 0);
;     p1 = __builtin_amdgcn_mfma_f32_32x32x16_bf16(b1, qr[d0], p1, 0, 0, 0); }
.LBB0_115:
	s_mov_b32 s32, 0
	s_mov_b32 s99, 0
	s_mov_b32 s98, 0
	v_add_u32_e32 v140, s52, v251
	v_add_u32_e32 v128, 0x28b00, v140
	v_add_u32_e32 v129, 0x28b80, v140
	v_add_u32_e32 v130, 0x28b08, v140
	v_add_u32_e32 v131, 0x28b88, v140
	v_add_u32_e32 v132, 0x28b20, v140
	v_add_u32_e32 v133, 0x28ba0, v140
	v_add_u32_e32 v134, 0x28b28, v140
	v_add_u32_e32 v135, 0x28ba8, v140
	v_add_u32_e32 v136, 0x28b40, v140
	v_add_u32_e32 v137, 0x28bc0, v140
	v_add_u32_e32 v138, 0x28b48, v140
	v_add_u32_e32 v139, 0x28bc8, v140
	v_add_u32_e32 v141, 0x28b60, v140
	v_add_u32_e32 v142, 0x28be0, v140
	v_add_u32_e32 v143, 0x28b68, v140
	ds_read2_b32 v[144:145], v128 offset1:1
	ds_read2_b32 v[128:129], v129 offset1:1
	ds_read2_b32 v[146:147], v130 offset1:1
	ds_read2_b32 v[130:131], v131 offset1:1
	ds_read2_b32 v[148:149], v132 offset1:1
	ds_read2_b32 v[132:133], v133 offset1:1
	ds_read2_b32 v[150:151], v134 offset1:1
	ds_read2_b32 v[134:135], v135 offset1:1
	ds_read2_b32 v[152:153], v136 offset1:1
	ds_read2_b32 v[136:137], v137 offset1:1
	ds_read2_b32 v[154:155], v138 offset1:1
	ds_read2_b32 v[138:139], v139 offset1:1
	v_add_u32_e32 v160, 0x28be8, v140
	ds_read2_b32 v[156:157], v141 offset1:1
	ds_read2_b32 v[140:141], v142 offset1:1
	ds_read2_b32 v[158:159], v143 offset1:1
	ds_read2_b32 v[142:143], v160 offset1:1
	s_waitcnt lgkmcnt(0)
	v_mov_b32_e32 v160, v145
.LBB0_118:
	s_add_i32 s8, s1, 0
	v_mov_b32_e32 v145, v160
	v_add3_u32 v160, s8, v236, v235
	ds_read_b128 v[194:197], v160
	ds_read_b128 v[198:201], v160 offset:8192
	v_add3_u32 v160, s8, v237, v235
	ds_read_b128 v[202:205], v160
	ds_read_b128 v[206:209], v160 offset:8192
	v_add3_u32 v160, s8, v238, v235
	s_waitcnt lgkmcnt(3)
	s_cmp_lg_u32 s32, 0
	s_cbranch_scc1 .Lc0B_far
	v_mfma_f32_32x32x16_bf16 v[144:159], v[194:197], v[162:165], v[144:159]
	ds_read_b128 v[194:197], v160
	s_waitcnt lgkmcnt(3)
	v_mfma_f32_32x32x16_bf16 v[128:143], v[198:201], v[162:165], v[128:143]
	s_branch .Lc0B_join
.Lc0B_far:
	v_mfma_f32_32x32x16_bf16 v[144:159], v[194:197], v[162:165], 0
	ds_read_b128 v[194:197], v160
	s_waitcnt lgkmcnt(3)
	v_mfma_f32_32x32x16_bf16 v[128:143], v[198:201], v[162:165], 0
.Lc0B_join:
	ds_read_b128 v[198:201], v160 offset:8192
	v_add3_u32 v160, s8, v239, v235
	s_waitcnt lgkmcnt(3)
	v_mfma_f32_32x32x16_bf16 v[144:159], v[202:205], v[166:169], v[144:159]
	ds_read_b128 v[202:205], v160
	s_waitcnt lgkmcnt(3)
	v_mfma_f32_32x32x16_bf16 v[128:143], v[206:209], v[166:169], v[128:143]
	ds_read_b128 v[206:209], v160 offset:8192
	v_add3_u32 v160, s8, v240, v235
	s_waitcnt lgkmcnt(3)
	v_mfma_f32_32x32x16_bf16 v[144:159], v[194:197], v[170:173], v[144:159]
	ds_read_b128 v[194:197], v160
	s_waitcnt lgkmcnt(3)
	v_mfma_f32_32x32x16_bf16 v[128:143], v[198:201], v[170:173], v[128:143]
	ds_read_b128 v[198:201], v160 offset:8192
	v_add3_u32 v160, s8, v241, v235
	s_waitcnt lgkmcnt(3)
	v_mfma_f32_32x32x16_bf16 v[144:159], v[202:205], v[174:177], v[144:159]
	ds_read_b128 v[202:205], v160
	s_waitcnt lgkmcnt(3)
	v_mfma_f32_32x32x16_bf16 v[128:143], v[206:209], v[174:177], v[128:143]
	ds_read_b128 v[206:209], v160 offset:8192
	v_add3_u32 v160, s8, v242, v235
	s_waitcnt lgkmcnt(3)
	v_mfma_f32_32x32x16_bf16 v[144:159], v[194:197], v[178:181], v[144:159]
	ds_read_b128 v[194:197], v160
	s_waitcnt lgkmcnt(3)
	v_mfma_f32_32x32x16_bf16 v[128:143], v[198:201], v[178:181], v[128:143]
	ds_read_b128 v[198:201], v160 offset:8192
	v_add3_u32 v160, s8, v243, v235
	s_waitcnt lgkmcnt(3)
	v_mfma_f32_32x32x16_bf16 v[144:159], v[202:205], v[182:185], v[144:159]
	ds_read_b128 v[202:205], v160
	s_waitcnt lgkmcnt(3)
	v_mfma_f32_32x32x16_bf16 v[128:143], v[206:209], v[182:185], v[128:143]
	ds_read_b128 v[206:209], v160 offset:8192
	s_waitcnt lgkmcnt(3)
	v_mfma_f32_32x32x16_bf16 v[144:159], v[194:197], v[186:189], v[144:159]
	s_waitcnt lgkmcnt(2)
	v_mfma_f32_32x32x16_bf16 v[128:143], v[198:201], v[186:189], v[128:143]
	s_waitcnt lgkmcnt(1)
	v_mfma_f32_32x32x16_bf16 v[144:159], v[202:205], v[190:193], v[144:159]
	s_waitcnt lgkmcnt(0)
	v_mfma_f32_32x32x16_bf16 v[128:143], v[206:209], v[190:193], v[128:143]
	s_setprio 0
	s_nop 9
	v_max_f32_e32 v160, v145, v145
	v_max_f32_e32 v194, v144, v144
	v_max_f32_e32 v160, v194, v160
	v_max3_f32 v160, v160, v146, v147
	v_max3_f32 v160, v160, v148, v149
	v_max3_f32 v160, v160, v150, v151
	v_max3_f32 v160, v160, v152, v153
	v_max3_f32 v160, v160, v154, v155
	v_max3_f32 v160, v160, v156, v157
	v_max3_f32 v160, v160, v158, v159
	v_max3_f32 v160, v160, v128, v129
	v_max3_f32 v160, v160, v130, v131
	v_max3_f32 v160, v160, v132, v133
	v_max3_f32 v160, v160, v134, v135
	v_max3_f32 v160, v160, v136, v137
	v_max3_f32 v160, v160, v138, v139
	v_max3_f32 v160, v160, v140, v141
	v_max3_f32 v160, v160, v142, v143
	v_mov_b32_e32 v194, v160
	s_nop 1
	v_permlane32_swap_b32_e32 v160, v194
	v_max_f32_e32 v194, v194, v194
	v_max_f32_e32 v160, v160, v160
	v_max_f32_e32 v160, v160, v194
	v_add_f32_e32 v160, s99, v160
	v_sub_f32_e32 v194, v160, v250
	v_cmp_ge_f32_e32 vcc, s53, v194
	v_max_f32_e32 v194, v250, v250
	v_max_f32_e32 v253, v194, v160
	v_sub_f32_e32 v160, v250, v253
	v_mul_f32_e32 v160, 0x3fb8aa3b, v160
	v_exp_f32_e32 v160, v160
	s_cmp_eq_u64 vcc, exec
	s_cselect_b64 s[8:9], -1, 0
	v_cndmask_b32_e64 v160, v160, 1.0, s[8:9]
	v_cmp_gt_f32_e32 vcc, 1.0, v160
	s_cbranch_vccz .LBB0_122
; __device__ __forceinline__ void partialSM(f32x16& p0, f32x16& p1, float& m_reg, float& mn, float& alpha) {
;     ...
;   float mnC = -mn * C;
; #pragma unroll
;   for (int r = 0; r < 16; ++r) p0[r] = fmaf(p0[r], C, mnC);
; #pragma unroll
;   for (int r = 0; r < 16; ++r) p1[r] = fmaf(p1[r], C, mnC);
; #pragma unroll
;   for (int r = 0; r < 16; ++r) p0[r] = __builtin_amdgcn_exp2f(p0[r]);
; }
; __device__ __forceinline__ void finishSM(f32x16& p0, f32x16& p1, float alpha, float& l_reg, bf16x8& pa0, bf16x8& pa1, bf16x8& pa2, bf16x8& pa3) {
; #pragma unroll
;   for (int r = 0; r < 16; ++r) p1[r] = __builtin_amdgcn_exp2f(p1[r]);
;   float ps = 0;
; #pragma unroll
;   for (int r = 0; r < 16; ++r) ps += p0[r];
; #pragma unroll
;   for (int r = 0; r < 16; ++r) ps += p1[r];
	s_and_saveexec_b64 s[10:11], s[6:7]
	v_lshl_add_u32 v194, v213, 2, s80
	ds_write_b32 v194, v160 offset:128
	s_or_b64 exec, exec, s[10:11]
	s_waitcnt lgkmcnt(0)
	v_add_u32_e32 v194, s80, v234
	ds_read_b128 v[206:209], v194 offset:224
	ds_read_b128 v[202:205], v194 offset:192
	ds_read_b128 v[198:201], v194 offset:160
	ds_read_b128 v[194:197], v194 offset:128
	s_waitcnt lgkmcnt(0)
	v_pk_mul_f32 v[108:109], v[108:109], v[206:207]
	v_pk_mul_f32 v[104:105], v[104:105], v[202:203]
	v_pk_mul_f32 v[100:101], v[100:101], v[198:199]
	v_pk_mul_f32 v[110:111], v[110:111], v[208:209]
	v_pk_mul_f32 v[106:107], v[106:107], v[204:205]
	v_pk_mul_f32 v[102:103], v[102:103], v[200:201]
	v_pk_mul_f32 v[98:99], v[98:99], v[196:197]
	v_pk_mul_f32 v[96:97], v[96:97], v[194:195]
	v_pk_mul_f32 v[124:125], v[124:125], v[206:207]
	v_pk_mul_f32 v[120:121], v[120:121], v[202:203]
	v_pk_mul_f32 v[116:117], v[116:117], v[198:199]
	v_pk_mul_f32 v[126:127], v[126:127], v[208:209]
	v_pk_mul_f32 v[122:123], v[122:123], v[204:205]
	v_pk_mul_f32 v[118:119], v[118:119], v[200:201]
	v_pk_mul_f32 v[114:115], v[114:115], v[196:197]
	v_pk_mul_f32 v[112:113], v[112:113], v[194:195]
	v_pk_mul_f32 v[92:93], v[92:93], v[206:207]
	v_pk_mul_f32 v[88:89], v[88:89], v[202:203]
	v_pk_mul_f32 v[84:85], v[84:85], v[198:199]
	v_pk_mul_f32 v[94:95], v[94:95], v[208:209]
	v_pk_mul_f32 v[90:91], v[90:91], v[204:205]
	v_pk_mul_f32 v[86:87], v[86:87], v[200:201]
	v_pk_mul_f32 v[82:83], v[82:83], v[196:197]
	v_pk_mul_f32 v[80:81], v[80:81], v[194:195]
	v_pk_mul_f32 v[76:77], v[76:77], v[206:207]
	v_pk_mul_f32 v[72:73], v[72:73], v[202:203]
	v_pk_mul_f32 v[68:69], v[68:69], v[198:199]
	v_pk_mul_f32 v[78:79], v[78:79], v[208:209]
	v_pk_mul_f32 v[74:75], v[74:75], v[204:205]
	v_pk_mul_f32 v[70:71], v[70:71], v[200:201]
	v_pk_mul_f32 v[66:67], v[66:67], v[196:197]
	v_pk_mul_f32 v[64:65], v[64:65], v[194:195]
	v_pk_mul_f32 v[60:61], v[60:61], v[206:207]
	v_pk_mul_f32 v[56:57], v[56:57], v[202:203]
	v_pk_mul_f32 v[52:53], v[52:53], v[198:199]
	v_pk_mul_f32 v[62:63], v[62:63], v[208:209]
	v_pk_mul_f32 v[58:59], v[58:59], v[204:205]
	v_pk_mul_f32 v[54:55], v[54:55], v[200:201]
	v_pk_mul_f32 v[50:51], v[50:51], v[196:197]
	v_pk_mul_f32 v[48:49], v[48:49], v[194:195]
	v_pk_mul_f32 v[44:45], v[44:45], v[206:207]
	v_pk_mul_f32 v[40:41], v[40:41], v[202:203]
	v_pk_mul_f32 v[36:37], v[36:37], v[198:199]
	v_pk_mul_f32 v[46:47], v[46:47], v[208:209]
	v_pk_mul_f32 v[42:43], v[42:43], v[204:205]
	v_pk_mul_f32 v[38:39], v[38:39], v[200:201]
	v_pk_mul_f32 v[34:35], v[34:35], v[196:197]
	v_pk_mul_f32 v[32:33], v[32:33], v[194:195]
	v_pk_mul_f32 v[28:29], v[28:29], v[206:207]
	v_pk_mul_f32 v[24:25], v[24:25], v[202:203]
	v_pk_mul_f32 v[20:21], v[20:21], v[198:199]
	v_pk_mul_f32 v[30:31], v[30:31], v[208:209]
	v_pk_mul_f32 v[26:27], v[26:27], v[204:205]
	v_pk_mul_f32 v[22:23], v[22:23], v[200:201]
	v_pk_mul_f32 v[18:19], v[18:19], v[196:197]
	v_pk_mul_f32 v[16:17], v[16:17], v[194:195]
	v_pk_mul_f32 v[12:13], v[12:13], v[206:207]
	v_pk_mul_f32 v[8:9], v[8:9], v[202:203]
	v_pk_mul_f32 v[4:5], v[4:5], v[198:199]
	v_pk_mul_f32 v[14:15], v[14:15], v[208:209]
	v_pk_mul_f32 v[10:11], v[10:11], v[204:205]
	v_pk_mul_f32 v[6:7], v[6:7], v[200:201]
	v_pk_mul_f32 v[2:3], v[2:3], v[196:197]
	v_pk_mul_f32 v[0:1], v[0:1], v[194:195]
.LBB0_122:
	v_cndmask_b32_e64 v250, v253, v250, s[8:9]
	v_mul_f32_e32 v194, 0xbfb8aa3b, v250
	v_add_f32_e32 v194, s98, v194
	v_fmamk_f32 v144, v144, 0x3fb8aa3b, v194
	v_fmamk_f32 v145, v145, 0x3fb8aa3b, v194
	v_fmamk_f32 v146, v146, 0x3fb8aa3b, v194
	v_fmamk_f32 v147, v147, 0x3fb8aa3b, v194
	v_fmamk_f32 v148, v148, 0x3fb8aa3b, v194
	v_fmamk_f32 v149, v149, 0x3fb8aa3b, v194
	v_fmamk_f32 v150, v150, 0x3fb8aa3b, v194
	v_fmamk_f32 v151, v151, 0x3fb8aa3b, v194
	v_fmamk_f32 v152, v152, 0x3fb8aa3b, v194
	v_fmamk_f32 v153, v153, 0x3fb8aa3b, v194
	v_fmamk_f32 v154, v154, 0x3fb8aa3b, v194
	v_fmamk_f32 v155, v155, 0x3fb8aa3b, v194
	v_fmamk_f32 v156, v156, 0x3fb8aa3b, v194
	v_fmamk_f32 v157, v157, 0x3fb8aa3b, v194
	v_fmamk_f32 v158, v158, 0x3fb8aa3b, v194
	v_fmamk_f32 v159, v159, 0x3fb8aa3b, v194
	v_fmamk_f32 v128, v128, 0x3fb8aa3b, v194
	v_fmamk_f32 v129, v129, 0x3fb8aa3b, v194
	v_fmamk_f32 v130, v130, 0x3fb8aa3b, v194
	v_fmamk_f32 v131, v131, 0x3fb8aa3b, v194
	v_fmamk_f32 v132, v132, 0x3fb8aa3b, v194
	v_fmamk_f32 v133, v133, 0x3fb8aa3b, v194
	v_fmamk_f32 v134, v134, 0x3fb8aa3b, v194
	v_fmamk_f32 v135, v135, 0x3fb8aa3b, v194
	v_fmamk_f32 v136, v136, 0x3fb8aa3b, v194
	v_fmamk_f32 v137, v137, 0x3fb8aa3b, v194
	v_fmamk_f32 v138, v138, 0x3fb8aa3b, v194
	v_fmamk_f32 v139, v139, 0x3fb8aa3b, v194
	v_fmamk_f32 v140, v140, 0x3fb8aa3b, v194
	v_fmamk_f32 v141, v141, 0x3fb8aa3b, v194
	v_fmamk_f32 v142, v142, 0x3fb8aa3b, v194
	v_fmac_f32_e32 v194, 0x3fb8aa3b, v143
	v_exp_f32_e32 v143, v144
	v_exp_f32_e32 v145, v145
	v_exp_f32_e32 v146, v146
	v_exp_f32_e32 v147, v147
	v_exp_f32_e32 v148, v148
	v_exp_f32_e32 v195, v128
	v_add_f32_e32 v128, 0, v143
	v_exp_f32_e32 v149, v149
	v_add_f32_e32 v128, v145, v128
	v_exp_f32_e32 v150, v150
	v_add_f32_e32 v128, v146, v128
	v_exp_f32_e32 v151, v151
	v_add_f32_e32 v128, v147, v128
	v_exp_f32_e32 v152, v152
	v_add_f32_e32 v128, v148, v128
	v_exp_f32_e32 v153, v153
	v_add_f32_e32 v128, v149, v128
	v_exp_f32_e32 v154, v154
	v_add_f32_e32 v128, v150, v128
	v_exp_f32_e32 v155, v155
	v_add_f32_e32 v128, v151, v128
	v_exp_f32_e32 v156, v156
	v_add_f32_e32 v128, v152, v128
	v_exp_f32_e32 v157, v157
	v_add_f32_e32 v128, v153, v128
	v_exp_f32_e32 v158, v158
	v_add_f32_e32 v128, v154, v128
	v_exp_f32_e32 v159, v159
	v_add_f32_e32 v128, v155, v128
	v_add_f32_e32 v128, v156, v128
	v_exp_f32_e32 v196, v129
; #define STEP_SYNC() do { asm volatile("s_waitcnt vmcnt(0) lgkmcnt(0)" ::: "memory"); __builtin_amdgcn_s_barrier(); asm volatile("" ::: "memory"); } while (0)
; #define ROT() do { bprev = bcur; bcur = bnext; bnext = (bnext + BUF_BYTES == NBUF * BUF_BYTES) ? 0 : bnext + BUF_BYTES; } while (0)
; __device__ __forceinline__ void finishSM(f32x16& p0, f32x16& p1, float alpha, float& l_reg, bf16x8& pa0, bf16x8& pa1, bf16x8& pa2, bf16x8& pa3) {
;     ...
;   for (int r = 0; r < 16; ++r) p1[r] = __builtin_amdgcn_exp2f(p1[r]);
;   float ps = 0;
; #pragma unroll
;   for (int r = 0; r < 16; ++r) ps += p0[r];
; #pragma unroll
;   for (int r = 0; r < 16; ++r) ps += p1[r];
;   { auto rr = __builtin_amdgcn_permlane32_swap(__float_as_uint(ps), __float_as_uint(ps), false, false);
;     ps = __uint_as_float(rr[0]) + __uint_as_float(rr[1]); }
;   l_reg = l_reg * alpha + ps;
;     ...
;   PK4(p0, 0, pa0); PK4(p0, 8, pa1); PK4(p1, 0, pa2); PK4(p1, 8, pa3);
; __device__ __forceinline__ void attn_pass(const bf16_t* __restrict__ Qb, const bf16_t* __restrict__ Kh, const bf16_t* __restrict__ Vh,
;                                           float* Ob, int mode, float lam, int qpos0, int seq, char* lds, const int wv, bf16_t* OBh) {
;     ...
;       STEP_SYNC();
;       ROT();
	v_add_f32_e32 v128, v157, v128
	v_exp_f32_e32 v197, v130
	v_add_f32_e32 v128, v158, v128
	v_exp_f32_e32 v198, v131
	v_add_f32_e32 v128, v159, v128
	v_exp_f32_e32 v199, v132
	v_add_f32_e32 v128, v195, v128
	v_exp_f32_e32 v200, v133
	v_add_f32_e32 v128, v196, v128
	v_exp_f32_e32 v201, v134
	v_add_f32_e32 v128, v197, v128
	v_exp_f32_e32 v202, v135
	v_add_f32_e32 v128, v198, v128
	v_exp_f32_e32 v203, v136
	v_add_f32_e32 v128, v199, v128
	v_exp_f32_e32 v204, v137
	v_add_f32_e32 v128, v200, v128
	v_exp_f32_e32 v205, v138
	v_add_f32_e32 v128, v201, v128
	v_exp_f32_e32 v206, v139
	v_add_f32_e32 v128, v202, v128
	v_exp_f32_e32 v207, v140
	v_add_f32_e32 v128, v203, v128
	v_exp_f32_e32 v208, v141
	v_add_f32_e32 v128, v204, v128
	v_exp_f32_e32 v209, v142
	v_add_f32_e32 v128, v205, v128
	v_exp_f32_e32 v194, v194
	v_add_f32_e32 v128, v206, v128
	v_add_f32_e32 v128, v207, v128
	v_add_f32_e32 v128, v208, v128
	v_add_f32_e32 v128, v209, v128
	v_add_f32_e32 v128, v194, v128
	v_mov_b32_e32 v129, v128
	s_nop 1
	v_permlane32_swap_b32_e32 v128, v129
	v_add_f32_e32 v144, v128, v129
	v_cvt_pk_bf16_f32 v128, v143, v145
	v_cvt_pk_bf16_f32 v129, v146, v147
	v_cvt_pk_bf16_f32 v130, v148, v149
	v_cvt_pk_bf16_f32 v131, v150, v151
	v_cvt_pk_bf16_f32 v132, v152, v153
	v_cvt_pk_bf16_f32 v133, v154, v155
	v_cvt_pk_bf16_f32 v134, v156, v157
	v_cvt_pk_bf16_f32 v135, v158, v159
	v_cvt_pk_bf16_f32 v136, v195, v196
	v_cvt_pk_bf16_f32 v137, v197, v198
	v_cvt_pk_bf16_f32 v138, v199, v200
	v_cvt_pk_bf16_f32 v139, v201, v202
	v_cvt_pk_bf16_f32 v140, v203, v204
	v_cvt_pk_bf16_f32 v141, v205, v206
	v_cvt_pk_bf16_f32 v142, v207, v208
	v_cvt_pk_bf16_f32 v143, v209, v194
	v_fmac_f32_e32 v144, v252, v160
	v_permlane32_swap_b32_e32 v128, v130
	v_permlane32_swap_b32_e32 v129, v131
	v_permlane32_swap_b32_e32 v132, v134
	v_permlane32_swap_b32_e32 v133, v135
	v_permlane32_swap_b32_e32 v136, v138
	v_permlane32_swap_b32_e32 v137, v139
	v_permlane32_swap_b32_e32 v140, v142
	v_permlane32_swap_b32_e32 v141, v143
	s_add_i32 s8, s65, 0xc000
	s_cmp_lg_u32 s8, 0x24000
	s_cselect_b32 s9, s8, 0
	s_addk_i32 s52, 0x100
	s_waitcnt vmcnt(0) lgkmcnt(0)
	s_barrier
	s_add_u32 s28, s28, 0xc0000
	s_addc_u32 s29, s29, 0
	s_add_i32 s77, s77, 64
	s_cmp_eq_u32 s52, 0
	s_cbranch_scc0 .LBB0_111
; #define SBAR() __builtin_amdgcn_sched_barrier(0)
; #define PV_LOAD(S, DD) do { S[0] = tr_read<v_off8(DD, 0, 0)>(vb); S[1] = tr_read<v_off8(DD, 0, 1)>(vb); S[2] = tr_read<v_off8(DD, 1, 0)>(vb); S[3] = tr_read<v_off8(DD, 1, 1)>(vb); \
;     S[4] = tr_read<v_off8(DD, 2, 0)>(vb); S[5] = tr_read<v_off8(DD, 2, 1)>(vb); S[6] = tr_read<v_off8(DD, 3, 0)>(vb); S[7] = tr_read<v_off8(DD, 3, 1)>(vb); } while (0)
; #define PV_MMA(OD, S) do { OD = __builtin_amdgcn_mfma_f32_32x32x16_bf16(pa0, PV_PK(S[0], S[1]), OD, 0, 0, 0); OD = __builtin_amdgcn_mfma_f32_32x32x16_bf16(pa1, PV_PK(S[2], S[3]), OD, 0, 0, 0); \
;     OD = __builtin_amdgcn_mfma_f32_32x32x16_bf16(pa2, PV_PK(S[4], S[5]), OD, 0, 0, 0); OD = __builtin_amdgcn_mfma_f32_32x32x16_bf16(pa3, PV_PK(S[6], S[7]), OD, 0, 0, 0); } while (0)
; #define PV_W8() do { asm volatile("s_waitcnt lgkmcnt(8)" ::: "memory"); SBAR(); } while (0)
; #define PV_W0() do { asm volatile("s_waitcnt lgkmcnt(0)" ::: "memory"); SBAR(); } while (0)
; __device__ __forceinline__ void pv8(f32x16* o, int vb, bf16x8 pa0, bf16x8 pa1, bf16x8 pa2, bf16x8 pa3) {
;   s16x4 A[8], B[8];
;   PV_LOAD(A, 0);
;   PV_LOAD(B, 1); PV_W8(); PV_MMA(o[0], A); SBAR();
;   PV_LOAD(A, 2); PV_W8(); PV_MMA(o[1], B); SBAR();
;   PV_LOAD(B, 3); PV_W8(); PV_MMA(o[2], A); SBAR();
;   PV_LOAD(A, 4); PV_W8(); PV_MMA(o[3], B); SBAR();
;   PV_LOAD(B, 5); PV_W8(); PV_MMA(o[4], A); SBAR();
;   PV_LOAD(A, 6); PV_W8(); PV_MMA(o[5], B); SBAR();
;   PV_LOAD(B, 7); PV_W8(); PV_MMA(o[6], A); SBAR();
;   PV_W0(); PV_MMA(o[7], B);
; }
; __device__ __forceinline__ void attn_pass(const bf16_t* __restrict__ Qb, const bf16_t* __restrict__ Kh, const bf16_t* __restrict__ Vh,
;                                           float* Ob, int mode, float lam, int qpos0, int seq, char* lds, const int wv, bf16_t* OBh) {
;     ...
;     pv8(o, vb0 + bprev, pa0, pa1, pa2, pa3);
	ds_read_b64_tr_b16 v[146:147], v226 offset:0
	ds_read_b64_tr_b16 v[148:149], v226 offset:0x800
	ds_read_b64_tr_b16 v[150:151], v226 offset:0x1000
	ds_read_b64_tr_b16 v[152:153], v226 offset:0x1800
	ds_read_b64_tr_b16 v[154:155], v226 offset:0x2000
	ds_read_b64_tr_b16 v[156:157], v226 offset:0x2800
	ds_read_b64_tr_b16 v[194:195], v226 offset:0x3000
	ds_read_b64_tr_b16 v[196:197], v226 offset:0x3800
	ds_read_b64_tr_b16 v[198:199], v226 offset:0x200
	ds_read_b64_tr_b16 v[200:201], v226 offset:0xa00
	ds_read_b64_tr_b16 v[202:203], v226 offset:0x1200
	ds_read_b64_tr_b16 v[204:205], v226 offset:0x1a00
	ds_read_b64_tr_b16 v[206:207], v226 offset:0x2200
	ds_read_b64_tr_b16 v[208:209], v226 offset:0x2a00
	ds_read_b64_tr_b16 v[218:219], v226 offset:0x3200
	ds_read_b64_tr_b16 v[220:221], v226 offset:0x3a00
	s_waitcnt lgkmcnt(8)
	s_nop 0
	v_mfma_f32_32x32x16_bf16 v[96:111], v[128:131], v[146:149], v[96:111]
	v_mfma_f32_32x32x16_bf16 v[96:111], v[132:135], v[150:153], v[96:111]
	v_mfma_f32_32x32x16_bf16 v[96:111], v[136:139], v[154:157], v[96:111]
	v_mfma_f32_32x32x16_bf16 v[96:111], v[140:143], v[194:197], v[96:111]
	ds_read_b64_tr_b16 v[146:147], v226 offset:0x400
	ds_read_b64_tr_b16 v[148:149], v226 offset:0xc00
	ds_read_b64_tr_b16 v[150:151], v226 offset:0x1400
	ds_read_b64_tr_b16 v[152:153], v226 offset:0x1c00
	ds_read_b64_tr_b16 v[154:155], v226 offset:0x2400
	ds_read_b64_tr_b16 v[156:157], v226 offset:0x2c00
	ds_read_b64_tr_b16 v[194:195], v226 offset:0x3400
	ds_read_b64_tr_b16 v[196:197], v226 offset:0x3c00
	s_waitcnt lgkmcnt(8)
	v_mfma_f32_32x32x16_bf16 v[112:127], v[128:131], v[198:201], v[112:127]
	v_mfma_f32_32x32x16_bf16 v[112:127], v[132:135], v[202:205], v[112:127]
	v_mfma_f32_32x32x16_bf16 v[112:127], v[136:139], v[206:209], v[112:127]
	v_mfma_f32_32x32x16_bf16 v[112:127], v[140:143], v[218:221], v[112:127]
	ds_read_b64_tr_b16 v[198:199], v226 offset:0x600
	ds_read_b64_tr_b16 v[200:201], v226 offset:0xe00
	ds_read_b64_tr_b16 v[202:203], v226 offset:0x1600
	ds_read_b64_tr_b16 v[204:205], v226 offset:0x1e00
	ds_read_b64_tr_b16 v[206:207], v226 offset:0x2600
	ds_read_b64_tr_b16 v[208:209], v226 offset:0x2e00
	ds_read_b64_tr_b16 v[218:219], v226 offset:0x3600
	ds_read_b64_tr_b16 v[220:221], v226 offset:0x3e00
	s_waitcnt lgkmcnt(8)
	v_mfma_f32_32x32x16_bf16 v[80:95], v[128:131], v[146:149], v[80:95]
	v_mfma_f32_32x32x16_bf16 v[80:95], v[132:135], v[150:153], v[80:95]
	v_mfma_f32_32x32x16_bf16 v[80:95], v[136:139], v[154:157], v[80:95]
	v_mfma_f32_32x32x16_bf16 v[80:95], v[140:143], v[194:197], v[80:95]
	ds_read_b64_tr_b16 v[146:147], v226 offset:0x4000
	ds_read_b64_tr_b16 v[148:149], v226 offset:0x4800
	ds_read_b64_tr_b16 v[150:151], v226 offset:0x5000
	ds_read_b64_tr_b16 v[152:153], v226 offset:0x5800
	ds_read_b64_tr_b16 v[154:155], v226 offset:0x6000
	ds_read_b64_tr_b16 v[156:157], v226 offset:0x6800
	ds_read_b64_tr_b16 v[194:195], v226 offset:0x7000
	ds_read_b64_tr_b16 v[196:197], v226 offset:0x7800
	s_waitcnt lgkmcnt(8)
	v_mfma_f32_32x32x16_bf16 v[64:79], v[128:131], v[198:201], v[64:79]
	v_mfma_f32_32x32x16_bf16 v[64:79], v[132:135], v[202:205], v[64:79]
	v_mfma_f32_32x32x16_bf16 v[64:79], v[136:139], v[206:209], v[64:79]
	v_mfma_f32_32x32x16_bf16 v[64:79], v[140:143], v[218:221], v[64:79]
	ds_read_b64_tr_b16 v[198:199], v226 offset:0x4200
	ds_read_b64_tr_b16 v[200:201], v226 offset:0x4a00
	ds_read_b64_tr_b16 v[202:203], v226 offset:0x5200
	ds_read_b64_tr_b16 v[204:205], v226 offset:0x5a00
	ds_read_b64_tr_b16 v[206:207], v226 offset:0x6200
	ds_read_b64_tr_b16 v[208:209], v226 offset:0x6a00
	ds_read_b64_tr_b16 v[218:219], v226 offset:0x7200
	ds_read_b64_tr_b16 v[220:221], v226 offset:0x7a00
	s_waitcnt lgkmcnt(8)
	v_mfma_f32_32x32x16_bf16 v[48:63], v[128:131], v[146:149], v[48:63]
	v_mfma_f32_32x32x16_bf16 v[48:63], v[132:135], v[150:153], v[48:63]
	v_mfma_f32_32x32x16_bf16 v[48:63], v[136:139], v[154:157], v[48:63]
	v_mfma_f32_32x32x16_bf16 v[48:63], v[140:143], v[194:197], v[48:63]
	ds_read_b64_tr_b16 v[146:147], v226 offset:0x4400
	ds_read_b64_tr_b16 v[148:149], v226 offset:0x4c00
	ds_read_b64_tr_b16 v[150:151], v226 offset:0x5400
	ds_read_b64_tr_b16 v[152:153], v226 offset:0x5c00
	ds_read_b64_tr_b16 v[154:155], v226 offset:0x6400
	ds_read_b64_tr_b16 v[156:157], v226 offset:0x6c00
	ds_read_b64_tr_b16 v[194:195], v226 offset:0x7400
	ds_read_b64_tr_b16 v[196:197], v226 offset:0x7c00
	s_waitcnt lgkmcnt(8)
	v_mfma_f32_32x32x16_bf16 v[32:47], v[128:131], v[198:201], v[32:47]
	v_mfma_f32_32x32x16_bf16 v[32:47], v[132:135], v[202:205], v[32:47]
	v_mfma_f32_32x32x16_bf16 v[32:47], v[136:139], v[206:209], v[32:47]
	v_mfma_f32_32x32x16_bf16 v[32:47], v[140:143], v[218:221], v[32:47]
	ds_read_b64_tr_b16 v[198:199], v226 offset:0x4600
	ds_read_b64_tr_b16 v[200:201], v226 offset:0x4e00
	ds_read_b64_tr_b16 v[202:203], v226 offset:0x5600
	ds_read_b64_tr_b16 v[204:205], v226 offset:0x5e00
	ds_read_b64_tr_b16 v[206:207], v226 offset:0x6600
	ds_read_b64_tr_b16 v[208:209], v226 offset:0x6e00
	ds_read_b64_tr_b16 v[218:219], v226 offset:0x7600
	ds_read_b64_tr_b16 v[220:221], v226 offset:0x7e00
	s_waitcnt lgkmcnt(8)
	v_mfma_f32_32x32x16_bf16 v[16:31], v[128:131], v[146:149], v[16:31]
	v_mfma_f32_32x32x16_bf16 v[16:31], v[132:135], v[150:153], v[16:31]
	v_mfma_f32_32x32x16_bf16 v[16:31], v[136:139], v[154:157], v[16:31]
	v_mfma_f32_32x32x16_bf16 v[16:31], v[140:143], v[194:197], v[16:31]
	s_waitcnt lgkmcnt(0)
	v_mfma_f32_32x32x16_bf16 v[0:15], v[128:131], v[198:201], v[0:15]
	s_mov_b64 s[8:9], 0
	v_mfma_f32_32x32x16_bf16 v[0:15], v[132:135], v[202:205], v[0:15]
	v_mfma_f32_32x32x16_bf16 v[0:15], v[136:139], v[206:209], v[0:15]
	v_mfma_f32_32x32x16_bf16 v[0:15], v[140:143], v[218:221], v[0:15]

; #define LAS __attribute__((address_space(3)))
; __device__ __forceinline__ void qkt(f32x16& p0, f32x16& p1, const char* Ks, const bf16x8* qr, int r32, int hi, const LAS float* tab, int rel0, int farmode) {
;   if (farmode != 0) { const float c = tab[farmode < 0 ? 0 : 384];
; #pragma unroll
;     for (int r = 0; r < 16; ++r) { p0[r] = c; p1[r] = c; }
;   } else {
;     const LAS float* tb = tab + (rel0 + 192 + 4 * hi);
; #pragma unroll
;     for (int r = 0; r < 16; ++r) { p0[r] = tb[(r & 3) + 8 * (r >> 2)]; p1[r] = tb[32 + (r & 3) + 8 * (r >> 2)]; }
;   }
; #pragma unroll
;   for (int d0 = 0; d0 < 8; ++d0) { int cb = (d0 * 16 + hi * 8) * 2;
;     bf16x8 b0 = *reinterpret_cast<const bf16x8*>(Ks + KSWZ(r32, cb));
;     bf16x8 b1 = *reinterpret_cast<const bf16x8*>(Ks + KSWZ(32 + r32, cb));
;     p0 = __builtin_amdgcn_mfma_f32_32x32x16_bf16(b0, qr[d0], p0, 0, 0, 0);
;     p1 = __builtin_amdgcn_mfma_f32_32x32x16_bf16(b1, qr[d0], p1, 0, 0, 0); }
.LBB0_128:
	s_setprio 1
	s_add_i32 s8, s1, 0x99
	s_cmpk_lt_u32 s8, 0x113
	s_cbranch_scc1 .LBB0_130
	s_cmpk_gt_i32 s1, 0xff66
	s_cselect_b32 s8, 0x600, 0
	s_add_i32 s8, s8, 0
	s_add_i32 s8, s8, 0x24800
	v_mov_b32_e32 v128, s8
	ds_read_b32 v160, v128
	s_mov_b32 s32, 1
	s_waitcnt vmcnt(0) lgkmcnt(0)
	v_mul_f32_e32 v128, 0x3fb8aa3b, v160
	v_readfirstlane_b32 s99, v160
	v_readfirstlane_b32 s98, v128
	s_branch .LBB0_133
.LBB0_130:
	s_mov_b32 s32, 0
	s_mov_b32 s99, 0
	s_mov_b32 s98, 0
	v_add_u32_e32 v140, s2, v250
	v_add_u32_e32 v128, 0x28b00, v140
	v_add_u32_e32 v129, 0x28b80, v140
	v_add_u32_e32 v130, 0x28b08, v140
	v_add_u32_e32 v131, 0x28b88, v140
	v_add_u32_e32 v132, 0x28b20, v140
	v_add_u32_e32 v133, 0x28ba0, v140
	v_add_u32_e32 v134, 0x28b28, v140
	v_add_u32_e32 v135, 0x28ba8, v140
	v_add_u32_e32 v136, 0x28b40, v140
	v_add_u32_e32 v137, 0x28bc0, v140
	v_add_u32_e32 v138, 0x28b48, v140
	v_add_u32_e32 v139, 0x28bc8, v140
	v_add_u32_e32 v141, 0x28b60, v140
	v_add_u32_e32 v142, 0x28be0, v140
	v_add_u32_e32 v143, 0x28b68, v140
	ds_read2_b32 v[144:145], v128 offset1:1
	ds_read2_b32 v[128:129], v129 offset1:1
	ds_read2_b32 v[146:147], v130 offset1:1
	ds_read2_b32 v[130:131], v131 offset1:1
	ds_read2_b32 v[148:149], v132 offset1:1
	ds_read2_b32 v[132:133], v133 offset1:1
	ds_read2_b32 v[150:151], v134 offset1:1
	ds_read2_b32 v[134:135], v135 offset1:1
	ds_read2_b32 v[152:153], v136 offset1:1
	ds_read2_b32 v[136:137], v137 offset1:1
	ds_read2_b32 v[154:155], v138 offset1:1
	ds_read2_b32 v[138:139], v139 offset1:1
	v_add_u32_e32 v160, 0x28be8, v140
	ds_read2_b32 v[156:157], v141 offset1:1
	ds_read2_b32 v[140:141], v142 offset1:1
	ds_read2_b32 v[158:159], v143 offset1:1
	ds_read2_b32 v[142:143], v160 offset1:1
	s_waitcnt lgkmcnt(0)
	v_mov_b32_e32 v160, v145
.LBB0_133:
	s_add_i32 s8, s24, 0
	v_mov_b32_e32 v145, v160
	v_add3_u32 v160, s8, v236, v235
	ds_read_b128 v[194:197], v160
	ds_read_b128 v[198:201], v160 offset:8192
	v_add3_u32 v160, s8, v237, v235
	ds_read_b128 v[202:205], v160
	ds_read_b128 v[206:209], v160 offset:8192
	v_add3_u32 v160, s8, v238, v235
	s_waitcnt lgkmcnt(3)
	s_cmp_lg_u32 s32, 0
	s_cbranch_scc1 .Lc0A_far
	v_mfma_f32_32x32x16_bf16 v[144:159], v[194:197], v[162:165], v[144:159]
	ds_read_b128 v[194:197], v160
	s_waitcnt lgkmcnt(3)
	v_mfma_f32_32x32x16_bf16 v[128:143], v[198:201], v[162:165], v[128:143]
	s_branch .Lc0A_join

; __device__ __forceinline__ void partialSM(f32x16& p0, f32x16& p1, float& m_reg, float& mn, float& alpha) {
;   constexpr float C = LOG2E;
;   float pmax = p0[0];
; #pragma unroll
;   for (int r = 1; r < 16; ++r) pmax = fmaxf(pmax, p0[r]);
; #pragma unroll
;   for (int r = 0; r < 16; ++r) pmax = fmaxf(pmax, p1[r]);
;   { auto rr = __builtin_amdgcn_permlane32_swap(__float_as_uint(pmax), __float_as_uint(pmax), false, false);
;     pmax = fmaxf(__uint_as_float(rr[0]), __uint_as_float(rr[1])); }
;   if (__builtin_expect(__all(pmax - m_reg <= THR), 1)) { mn = m_reg; alpha = 1.f; }
;   else { mn = fmaxf(m_reg, pmax); alpha = __builtin_amdgcn_exp2f((m_reg - mn) * C); m_reg = mn; }
; __device__ __forceinline__ void qkt(f32x16& p0, f32x16& p1, const char* Ks, const bf16x8* qr, int r32, int hi, const LAS float* tab, int rel0, int farmode) {
;     ...
;   for (int d0 = 0; d0 < 8; ++d0) { int cb = (d0 * 16 + hi * 8) * 2;
;     bf16x8 b0 = *reinterpret_cast<const bf16x8*>(Ks + KSWZ(r32, cb));
;     bf16x8 b1 = *reinterpret_cast<const bf16x8*>(Ks + KSWZ(32 + r32, cb));
;     p0 = __builtin_amdgcn_mfma_f32_32x32x16_bf16(b0, qr[d0], p0, 0, 0, 0);
;     p1 = __builtin_amdgcn_mfma_f32_32x32x16_bf16(b1, qr[d0], p1, 0, 0, 0); }
.Lc0A_join:
	ds_read_b128 v[198:201], v160 offset:8192
	v_add3_u32 v160, s8, v239, v235
	s_waitcnt lgkmcnt(3)
	v_mfma_f32_32x32x16_bf16 v[144:159], v[202:205], v[166:169], v[144:159]
	ds_read_b128 v[202:205], v160
	s_waitcnt lgkmcnt(3)
	v_mfma_f32_32x32x16_bf16 v[128:143], v[206:209], v[166:169], v[128:143]
	ds_read_b128 v[206:209], v160 offset:8192
	v_add3_u32 v160, s8, v240, v235
	s_waitcnt lgkmcnt(3)
	v_mfma_f32_32x32x16_bf16 v[144:159], v[194:197], v[170:173], v[144:159]
	ds_read_b128 v[194:197], v160
	s_waitcnt lgkmcnt(3)
	v_mfma_f32_32x32x16_bf16 v[128:143], v[198:201], v[170:173], v[128:143]
	ds_read_b128 v[198:201], v160 offset:8192
	v_add3_u32 v160, s8, v241, v235
	s_waitcnt lgkmcnt(3)
	v_mfma_f32_32x32x16_bf16 v[144:159], v[202:205], v[174:177], v[144:159]
	ds_read_b128 v[202:205], v160
	s_waitcnt lgkmcnt(3)
	v_mfma_f32_32x32x16_bf16 v[128:143], v[206:209], v[174:177], v[128:143]
	ds_read_b128 v[206:209], v160 offset:8192
	v_add3_u32 v160, s8, v242, v235
	s_waitcnt lgkmcnt(3)
	v_mfma_f32_32x32x16_bf16 v[144:159], v[194:197], v[178:181], v[144:159]
	ds_read_b128 v[194:197], v160
	s_waitcnt lgkmcnt(3)
	v_mfma_f32_32x32x16_bf16 v[128:143], v[198:201], v[178:181], v[128:143]
	ds_read_b128 v[198:201], v160 offset:8192
	v_add3_u32 v160, s8, v243, v235
	s_waitcnt lgkmcnt(3)
	v_mfma_f32_32x32x16_bf16 v[144:159], v[202:205], v[182:185], v[144:159]
	ds_read_b128 v[202:205], v160
	s_waitcnt lgkmcnt(3)
	v_mfma_f32_32x32x16_bf16 v[128:143], v[206:209], v[182:185], v[128:143]
	ds_read_b128 v[206:209], v160 offset:8192
	s_waitcnt lgkmcnt(3)
	v_mfma_f32_32x32x16_bf16 v[144:159], v[194:197], v[186:189], v[144:159]
	s_waitcnt lgkmcnt(2)
	v_mfma_f32_32x32x16_bf16 v[128:143], v[198:201], v[186:189], v[128:143]
	s_waitcnt lgkmcnt(1)
	v_mfma_f32_32x32x16_bf16 v[144:159], v[202:205], v[190:193], v[144:159]
	s_waitcnt lgkmcnt(0)
	v_mfma_f32_32x32x16_bf16 v[128:143], v[206:209], v[190:193], v[128:143]
	s_setprio 0
	s_nop 9
	v_max_f32_e32 v160, v145, v145
	v_max_f32_e32 v194, v144, v144
	v_max_f32_e32 v160, v194, v160
	v_max3_f32 v160, v160, v146, v147
	v_max3_f32 v160, v160, v148, v149
	v_max3_f32 v160, v160, v150, v151
	v_max3_f32 v160, v160, v152, v153
	v_max3_f32 v160, v160, v154, v155
	v_max3_f32 v160, v160, v156, v157
	v_max3_f32 v160, v160, v158, v159
	v_max3_f32 v160, v160, v128, v129
	v_max3_f32 v160, v160, v130, v131
	v_max3_f32 v160, v160, v132, v133
	v_max3_f32 v160, v160, v134, v135
	v_max3_f32 v160, v160, v136, v137
	v_max3_f32 v160, v160, v138, v139
	v_max3_f32 v160, v160, v140, v141
	v_max3_f32 v160, v160, v142, v143
	v_mov_b32_e32 v194, v160
	s_nop 1
	v_permlane32_swap_b32_e32 v160, v194
	v_max_f32_e32 v194, v194, v194
	v_max_f32_e32 v160, v160, v160
	v_max_f32_e32 v160, v160, v194
	v_add_f32_e32 v160, s99, v160
	v_sub_f32_e32 v194, v160, v227
	v_cmp_ge_f32_e32 vcc, s53, v194
	v_max_f32_e32 v194, v227, v227
	v_max_f32_e32 v229, v194, v160
	v_sub_f32_e32 v160, v227, v229
	v_mul_f32_e32 v160, 0x3fb8aa3b, v160
	v_exp_f32_e32 v160, v160
	s_cmp_eq_u64 vcc, exec
	s_cselect_b64 s[8:9], -1, 0
	v_cndmask_b32_e64 v160, v160, 1.0, s[8:9]
	v_cmp_gt_f32_e32 vcc, 1.0, v160
	s_cbranch_vccz .LBB0_137
	s_and_saveexec_b64 s[10:11], s[6:7]
	ds_write_b32 v234, v160 offset:128
	s_or_b64 exec, exec, s[10:11]
	s_waitcnt lgkmcnt(0)
	v_add_u32_e32 v194, s80, v216
	ds_read_b128 v[206:209], v194 offset:224
	ds_read_b128 v[202:205], v194 offset:192
	ds_read_b128 v[198:201], v194 offset:160
	ds_read_b128 v[194:197], v194 offset:128
	s_waitcnt lgkmcnt(3)
	v_pk_mul_f32 v[108:109], v[108:109], v[206:207]
	s_waitcnt lgkmcnt(2)
	v_pk_mul_f32 v[104:105], v[104:105], v[202:203]
	s_waitcnt lgkmcnt(1)
	v_pk_mul_f32 v[100:101], v[100:101], v[198:199]
	v_pk_mul_f32 v[110:111], v[110:111], v[208:209]
	v_pk_mul_f32 v[106:107], v[106:107], v[204:205]
	v_pk_mul_f32 v[102:103], v[102:103], v[200:201]
	s_waitcnt lgkmcnt(0)
	v_pk_mul_f32 v[98:99], v[98:99], v[196:197]
	v_pk_mul_f32 v[96:97], v[96:97], v[194:195]
	v_pk_mul_f32 v[124:125], v[124:125], v[206:207]
	v_pk_mul_f32 v[120:121], v[120:121], v[202:203]
	v_pk_mul_f32 v[116:117], v[116:117], v[198:199]
	v_pk_mul_f32 v[126:127], v[126:127], v[208:209]
	v_pk_mul_f32 v[122:123], v[122:123], v[204:205]
	v_pk_mul_f32 v[118:119], v[118:119], v[200:201]
	v_pk_mul_f32 v[114:115], v[114:115], v[196:197]
	v_pk_mul_f32 v[112:113], v[112:113], v[194:195]
	v_pk_mul_f32 v[92:93], v[92:93], v[206:207]
	v_pk_mul_f32 v[88:89], v[88:89], v[202:203]
	v_pk_mul_f32 v[84:85], v[84:85], v[198:199]
	v_pk_mul_f32 v[94:95], v[94:95], v[208:209]
	v_pk_mul_f32 v[90:91], v[90:91], v[204:205]
	v_pk_mul_f32 v[86:87], v[86:87], v[200:201]
	v_pk_mul_f32 v[82:83], v[82:83], v[196:197]
	v_pk_mul_f32 v[80:81], v[80:81], v[194:195]
	v_pk_mul_f32 v[76:77], v[76:77], v[206:207]
	v_pk_mul_f32 v[72:73], v[72:73], v[202:203]
	v_pk_mul_f32 v[68:69], v[68:69], v[198:199]
	v_pk_mul_f32 v[78:79], v[78:79], v[208:209]
	v_pk_mul_f32 v[74:75], v[74:75], v[204:205]
	v_pk_mul_f32 v[70:71], v[70:71], v[200:201]
	v_pk_mul_f32 v[66:67], v[66:67], v[196:197]
	v_pk_mul_f32 v[64:65], v[64:65], v[194:195]
	v_pk_mul_f32 v[60:61], v[60:61], v[206:207]
	v_pk_mul_f32 v[56:57], v[56:57], v[202:203]
	v_pk_mul_f32 v[52:53], v[52:53], v[198:199]
	v_pk_mul_f32 v[62:63], v[62:63], v[208:209]
	v_pk_mul_f32 v[58:59], v[58:59], v[204:205]
	v_pk_mul_f32 v[54:55], v[54:55], v[200:201]
	v_pk_mul_f32 v[50:51], v[50:51], v[196:197]
	v_pk_mul_f32 v[48:49], v[48:49], v[194:195]
	v_pk_mul_f32 v[44:45], v[44:45], v[206:207]
	v_pk_mul_f32 v[40:41], v[40:41], v[202:203]
	v_pk_mul_f32 v[36:37], v[36:37], v[198:199]
	v_pk_mul_f32 v[46:47], v[46:47], v[208:209]
	v_pk_mul_f32 v[42:43], v[42:43], v[204:205]
	v_pk_mul_f32 v[38:39], v[38:39], v[200:201]
	v_pk_mul_f32 v[34:35], v[34:35], v[196:197]
	v_pk_mul_f32 v[32:33], v[32:33], v[194:195]
	v_pk_mul_f32 v[28:29], v[28:29], v[206:207]
	v_pk_mul_f32 v[24:25], v[24:25], v[202:203]
	v_pk_mul_f32 v[20:21], v[20:21], v[198:199]
	v_pk_mul_f32 v[30:31], v[30:31], v[208:209]
	v_pk_mul_f32 v[26:27], v[26:27], v[204:205]
	v_pk_mul_f32 v[22:23], v[22:23], v[200:201]
	v_pk_mul_f32 v[18:19], v[18:19], v[196:197]
	v_pk_mul_f32 v[16:17], v[16:17], v[194:195]
	v_pk_mul_f32 v[12:13], v[12:13], v[206:207]
	v_pk_mul_f32 v[8:9], v[8:9], v[202:203]
	v_pk_mul_f32 v[4:5], v[4:5], v[198:199]
	v_pk_mul_f32 v[14:15], v[14:15], v[208:209]
	v_pk_mul_f32 v[10:11], v[10:11], v[204:205]
	v_pk_mul_f32 v[6:7], v[6:7], v[200:201]
	v_pk_mul_f32 v[2:3], v[2:3], v[196:197]
	v_pk_mul_f32 v[0:1], v[0:1], v[194:195]
; #define SBAR() __builtin_amdgcn_sched_barrier(0)
; #define PV_LOAD(S, DD) do { S[0] = tr_read<v_off8(DD, 0, 0)>(vb); S[1] = tr_read<v_off8(DD, 0, 1)>(vb); S[2] = tr_read<v_off8(DD, 1, 0)>(vb); S[3] = tr_read<v_off8(DD, 1, 1)>(vb); \
;     S[4] = tr_read<v_off8(DD, 2, 0)>(vb); S[5] = tr_read<v_off8(DD, 2, 1)>(vb); S[6] = tr_read<v_off8(DD, 3, 0)>(vb); S[7] = tr_read<v_off8(DD, 3, 1)>(vb); } while (0)
; #define PV_MMA(OD, S) do { OD = __builtin_amdgcn_mfma_f32_32x32x16_bf16(pa0, PV_PK(S[0], S[1]), OD, 0, 0, 0); OD = __builtin_amdgcn_mfma_f32_32x32x16_bf16(pa1, PV_PK(S[2], S[3]), OD, 0, 0, 0); \
;     OD = __builtin_amdgcn_mfma_f32_32x32x16_bf16(pa2, PV_PK(S[4], S[5]), OD, 0, 0, 0); OD = __builtin_amdgcn_mfma_f32_32x32x16_bf16(pa3, PV_PK(S[6], S[7]), OD, 0, 0, 0); } while (0)
; #define PV_W8() do { asm volatile("s_waitcnt lgkmcnt(8)" ::: "memory"); SBAR(); } while (0)
; __device__ __forceinline__ void partialSM(f32x16& p0, f32x16& p1, float& m_reg, float& mn, float& alpha) {
;     ...
;   float mnC = -mn * C;
; #pragma unroll
;   for (int r = 0; r < 16; ++r) p0[r] = fmaf(p0[r], C, mnC);
; #pragma unroll
;   for (int r = 0; r < 16; ++r) p1[r] = fmaf(p1[r], C, mnC);
; #pragma unroll
;   for (int r = 0; r < 16; ++r) p0[r] = __builtin_amdgcn_exp2f(p0[r]);
; }
; __device__ __forceinline__ void finishSM(f32x16& p0, f32x16& p1, float alpha, float& l_reg, bf16x8& pa0, bf16x8& pa1, bf16x8& pa2, bf16x8& pa3) {
; #pragma unroll
;   for (int r = 0; r < 16; ++r) p1[r] = __builtin_amdgcn_exp2f(p1[r]);
;   float ps = 0;
; #pragma unroll
;   for (int r = 0; r < 16; ++r) ps += p0[r];
; #pragma unroll
;   for (int r = 0; r < 16; ++r) ps += p1[r];
;   { auto rr = __builtin_amdgcn_permlane32_swap(__float_as_uint(ps), __float_as_uint(ps), false, false);
;     ps = __uint_as_float(rr[0]) + __uint_as_float(rr[1]); }
;   l_reg = l_reg * alpha + ps;
;     ...
;   PK4(p0, 0, pa0); PK4(p0, 8, pa1); PK4(p1, 0, pa2); PK4(p1, 8, pa3);
; __device__ __forceinline__ void pv8(f32x16* o, int vb, bf16x8 pa0, bf16x8 pa1, bf16x8 pa2, bf16x8 pa3) {
;   s16x4 A[8], B[8];
;   PV_LOAD(A, 0);
;   PV_LOAD(B, 1); PV_W8(); PV_MMA(o[0], A); SBAR();
;   PV_LOAD(A, 2); PV_W8(); PV_MMA(o[1], B); SBAR();
.LBB0_137:
	v_cndmask_b32_e64 v227, v229, v227, s[8:9]
	v_mul_f32_e32 v194, 0xbfb8aa3b, v227
	v_add_f32_e32 v194, s98, v194
	v_fmamk_f32 v144, v144, 0x3fb8aa3b, v194
	v_fmamk_f32 v145, v145, 0x3fb8aa3b, v194
	v_fmamk_f32 v146, v146, 0x3fb8aa3b, v194
	v_fmamk_f32 v147, v147, 0x3fb8aa3b, v194
	v_fmamk_f32 v148, v148, 0x3fb8aa3b, v194
	v_fmamk_f32 v149, v149, 0x3fb8aa3b, v194
	v_fmamk_f32 v150, v150, 0x3fb8aa3b, v194
	v_fmamk_f32 v151, v151, 0x3fb8aa3b, v194
	v_fmamk_f32 v152, v152, 0x3fb8aa3b, v194
	v_fmamk_f32 v153, v153, 0x3fb8aa3b, v194
	v_fmamk_f32 v154, v154, 0x3fb8aa3b, v194
	v_fmamk_f32 v155, v155, 0x3fb8aa3b, v194
	v_fmamk_f32 v156, v156, 0x3fb8aa3b, v194
	v_fmamk_f32 v157, v157, 0x3fb8aa3b, v194
	v_fmamk_f32 v158, v158, 0x3fb8aa3b, v194
	v_fmamk_f32 v159, v159, 0x3fb8aa3b, v194
	v_fmamk_f32 v128, v128, 0x3fb8aa3b, v194
	v_fmamk_f32 v129, v129, 0x3fb8aa3b, v194
	v_fmamk_f32 v130, v130, 0x3fb8aa3b, v194
	v_fmamk_f32 v131, v131, 0x3fb8aa3b, v194
	v_fmamk_f32 v132, v132, 0x3fb8aa3b, v194
	v_fmamk_f32 v133, v133, 0x3fb8aa3b, v194
	v_fmamk_f32 v134, v134, 0x3fb8aa3b, v194
	v_fmamk_f32 v135, v135, 0x3fb8aa3b, v194
	v_fmamk_f32 v136, v136, 0x3fb8aa3b, v194
	v_fmamk_f32 v137, v137, 0x3fb8aa3b, v194
	v_fmamk_f32 v138, v138, 0x3fb8aa3b, v194
	v_fmamk_f32 v139, v139, 0x3fb8aa3b, v194
	v_fmamk_f32 v140, v140, 0x3fb8aa3b, v194
	v_fmamk_f32 v141, v141, 0x3fb8aa3b, v194
	v_fmamk_f32 v142, v142, 0x3fb8aa3b, v194
	v_fmac_f32_e32 v194, 0x3fb8aa3b, v143
	v_exp_f32_e32 v143, v144
	v_exp_f32_e32 v145, v145
	v_exp_f32_e32 v146, v146
	v_exp_f32_e32 v147, v147
	v_exp_f32_e32 v148, v148
	v_exp_f32_e32 v195, v128
	v_add_f32_e32 v128, 0, v143
	v_exp_f32_e32 v149, v149
	v_add_f32_e32 v128, v145, v128
	v_exp_f32_e32 v150, v150
	v_add_f32_e32 v128, v146, v128
	v_exp_f32_e32 v151, v151
	v_add_f32_e32 v128, v147, v128
	v_exp_f32_e32 v152, v152
	v_add_f32_e32 v128, v148, v128
	v_exp_f32_e32 v153, v153
	v_add_f32_e32 v128, v149, v128
	v_exp_f32_e32 v154, v154
	v_add_f32_e32 v128, v150, v128
	v_exp_f32_e32 v155, v155
	v_add_f32_e32 v128, v151, v128
	v_exp_f32_e32 v156, v156
	v_add_f32_e32 v128, v152, v128
	v_exp_f32_e32 v157, v157
	v_add_f32_e32 v128, v153, v128
	v_exp_f32_e32 v158, v158
	v_add_f32_e32 v128, v154, v128
	v_exp_f32_e32 v159, v159
	v_add_f32_e32 v128, v155, v128
	v_add_f32_e32 v128, v156, v128
	v_exp_f32_e32 v196, v129
	v_add_f32_e32 v128, v157, v128
	v_exp_f32_e32 v197, v130
	v_add_f32_e32 v128, v158, v128
	v_exp_f32_e32 v198, v131
	v_add_f32_e32 v128, v159, v128
	v_exp_f32_e32 v199, v132
	v_add_f32_e32 v128, v195, v128
	v_exp_f32_e32 v200, v133
	v_add_f32_e32 v128, v196, v128
	v_exp_f32_e32 v201, v134
	v_add_f32_e32 v128, v197, v128
	v_exp_f32_e32 v202, v135
	v_add_f32_e32 v128, v198, v128
	v_exp_f32_e32 v203, v136
	v_add_f32_e32 v128, v199, v128
	v_exp_f32_e32 v204, v137
	v_add_f32_e32 v128, v200, v128
	v_exp_f32_e32 v205, v138
	v_add_f32_e32 v128, v201, v128
	v_exp_f32_e32 v206, v139
	v_add_f32_e32 v128, v202, v128
	v_exp_f32_e32 v207, v140
	v_add_f32_e32 v128, v203, v128
	v_exp_f32_e32 v208, v141
	v_add_f32_e32 v128, v204, v128
	v_exp_f32_e32 v209, v142
	v_add_f32_e32 v128, v205, v128
	v_exp_f32_e32 v194, v194
	v_add_f32_e32 v128, v206, v128
	v_add_f32_e32 v128, v207, v128
	v_add_f32_e32 v128, v208, v128
	v_add_f32_e32 v128, v209, v128
	v_add_f32_e32 v128, v194, v128
	v_mov_b32_e32 v129, v128
	s_nop 1
	v_permlane32_swap_b32_e32 v128, v129
	v_add_f32_e32 v144, v128, v129
	v_fmac_f32_e32 v144, v228, v160
	v_cvt_pk_bf16_f32 v128, v143, v145
	v_cvt_pk_bf16_f32 v129, v146, v147
	v_cvt_pk_bf16_f32 v130, v148, v149
	v_cvt_pk_bf16_f32 v131, v150, v151
	v_cvt_pk_bf16_f32 v132, v152, v153
	v_cvt_pk_bf16_f32 v133, v154, v155
	v_cvt_pk_bf16_f32 v134, v156, v157
	v_cvt_pk_bf16_f32 v135, v158, v159
	v_cvt_pk_bf16_f32 v136, v195, v196
	v_cvt_pk_bf16_f32 v137, v197, v198
	v_cvt_pk_bf16_f32 v138, v199, v200
	v_cvt_pk_bf16_f32 v139, v201, v202
	v_cvt_pk_bf16_f32 v140, v203, v204
	v_cvt_pk_bf16_f32 v141, v205, v206
	v_cvt_pk_bf16_f32 v142, v207, v208
	v_cvt_pk_bf16_f32 v143, v209, v194
	s_nop 0
	v_permlane32_swap_b32_e32 v128, v130
	v_permlane32_swap_b32_e32 v129, v131
	v_permlane32_swap_b32_e32 v132, v134
	v_permlane32_swap_b32_e32 v133, v135
	v_permlane32_swap_b32_e32 v136, v138
	v_permlane32_swap_b32_e32 v137, v139
	v_permlane32_swap_b32_e32 v140, v142
	v_permlane32_swap_b32_e32 v141, v143
	s_setprio 1
	v_add_u32_e32 v145, s24, v226
	ds_read_b64_tr_b16 v[146:147], v145 offset:0
	ds_read_b64_tr_b16 v[148:149], v145 offset:0x800
	ds_read_b64_tr_b16 v[150:151], v145 offset:0x1000
	ds_read_b64_tr_b16 v[152:153], v145 offset:0x1800
	ds_read_b64_tr_b16 v[154:155], v145 offset:0x2000
	ds_read_b64_tr_b16 v[156:157], v145 offset:0x2800
	ds_read_b64_tr_b16 v[194:195], v145 offset:0x3000
	ds_read_b64_tr_b16 v[196:197], v145 offset:0x3800
	ds_read_b64_tr_b16 v[198:199], v145 offset:0x200
	ds_read_b64_tr_b16 v[200:201], v145 offset:0xa00
	ds_read_b64_tr_b16 v[202:203], v145 offset:0x1200
	ds_read_b64_tr_b16 v[204:205], v145 offset:0x1a00
	ds_read_b64_tr_b16 v[206:207], v145 offset:0x2200
	ds_read_b64_tr_b16 v[208:209], v145 offset:0x2a00
	ds_read_b64_tr_b16 v[228:229], v145 offset:0x3200
	ds_read_b64_tr_b16 v[230:231], v145 offset:0x3a00
	s_waitcnt lgkmcnt(8)
; #define SBAR() __builtin_amdgcn_sched_barrier(0)
; #define PV_LOAD(S, DD) do { S[0] = tr_read<v_off8(DD, 0, 0)>(vb); S[1] = tr_read<v_off8(DD, 0, 1)>(vb); S[2] = tr_read<v_off8(DD, 1, 0)>(vb); S[3] = tr_read<v_off8(DD, 1, 1)>(vb); \
;     S[4] = tr_read<v_off8(DD, 2, 0)>(vb); S[5] = tr_read<v_off8(DD, 2, 1)>(vb); S[6] = tr_read<v_off8(DD, 3, 0)>(vb); S[7] = tr_read<v_off8(DD, 3, 1)>(vb); } while (0)
; #define PV_MMA(OD, S) do { OD = __builtin_amdgcn_mfma_f32_32x32x16_bf16(pa0, PV_PK(S[0], S[1]), OD, 0, 0, 0); OD = __builtin_amdgcn_mfma_f32_32x32x16_bf16(pa1, PV_PK(S[2], S[3]), OD, 0, 0, 0); \
;     OD = __builtin_amdgcn_mfma_f32_32x32x16_bf16(pa2, PV_PK(S[4], S[5]), OD, 0, 0, 0); OD = __builtin_amdgcn_mfma_f32_32x32x16_bf16(pa3, PV_PK(S[6], S[7]), OD, 0, 0, 0); } while (0)
; #define PV_W8() do { asm volatile("s_waitcnt lgkmcnt(8)" ::: "memory"); SBAR(); } while (0)
; #define PV_W0() do { asm volatile("s_waitcnt lgkmcnt(0)" ::: "memory"); SBAR(); } while (0)
; #define STEP_SYNC() do { asm volatile("s_waitcnt vmcnt(0) lgkmcnt(0)" ::: "memory"); __builtin_amdgcn_s_barrier(); asm volatile("" ::: "memory"); } while (0)
; #define ROT() do { bprev = bcur; bcur = bnext; bnext = (bnext + BUF_BYTES == NBUF * BUF_BYTES) ? 0 : bnext + BUF_BYTES; } while (0)
; __device__ __forceinline__ void pv8(f32x16* o, int vb, bf16x8 pa0, bf16x8 pa1, bf16x8 pa2, bf16x8 pa3) {
;   s16x4 A[8], B[8];
;   PV_LOAD(A, 0);
;   PV_LOAD(B, 1); PV_W8(); PV_MMA(o[0], A); SBAR();
;   PV_LOAD(A, 2); PV_W8(); PV_MMA(o[1], B); SBAR();
;   PV_LOAD(B, 3); PV_W8(); PV_MMA(o[2], A); SBAR();
;   PV_LOAD(A, 4); PV_W8(); PV_MMA(o[3], B); SBAR();
;   PV_LOAD(B, 5); PV_W8(); PV_MMA(o[4], A); SBAR();
;   PV_LOAD(A, 6); PV_W8(); PV_MMA(o[5], B); SBAR();
;   PV_LOAD(B, 7); PV_W8(); PV_MMA(o[6], A); SBAR();
;   PV_W0(); PV_MMA(o[7], B);
; }
; __device__ __forceinline__ void attn_pass(const bf16_t* __restrict__ Qb, const bf16_t* __restrict__ Kh, const bf16_t* __restrict__ Vh,
;                                           float* Ob, int mode, float lam, int qpos0, int seq, char* lds, const int wv, bf16_t* OBh) {
;     ...
;       pv8(o, vb0 + bcur, pa0, pa1, pa2, pa3);
;       __builtin_amdgcn_s_setprio(0);
;       STEP_SYNC();
;       ROT();
	s_nop 0
	v_mfma_f32_32x32x16_bf16 v[96:111], v[128:131], v[146:149], v[96:111]
	v_mfma_f32_32x32x16_bf16 v[96:111], v[132:135], v[150:153], v[96:111]
	v_mfma_f32_32x32x16_bf16 v[96:111], v[136:139], v[154:157], v[96:111]
	v_mfma_f32_32x32x16_bf16 v[96:111], v[140:143], v[194:197], v[96:111]
	ds_read_b64_tr_b16 v[146:147], v145 offset:0x400
	ds_read_b64_tr_b16 v[148:149], v145 offset:0xc00
	ds_read_b64_tr_b16 v[150:151], v145 offset:0x1400
	ds_read_b64_tr_b16 v[152:153], v145 offset:0x1c00
	ds_read_b64_tr_b16 v[154:155], v145 offset:0x2400
	ds_read_b64_tr_b16 v[156:157], v145 offset:0x2c00
	ds_read_b64_tr_b16 v[194:195], v145 offset:0x3400
	ds_read_b64_tr_b16 v[196:197], v145 offset:0x3c00
	s_waitcnt lgkmcnt(8)
	v_mfma_f32_32x32x16_bf16 v[112:127], v[128:131], v[198:201], v[112:127]
	v_mfma_f32_32x32x16_bf16 v[112:127], v[132:135], v[202:205], v[112:127]
	v_mfma_f32_32x32x16_bf16 v[112:127], v[136:139], v[206:209], v[112:127]
	v_mfma_f32_32x32x16_bf16 v[112:127], v[140:143], v[228:231], v[112:127]
	ds_read_b64_tr_b16 v[198:199], v145 offset:0x600
	ds_read_b64_tr_b16 v[200:201], v145 offset:0xe00
	ds_read_b64_tr_b16 v[202:203], v145 offset:0x1600
	ds_read_b64_tr_b16 v[204:205], v145 offset:0x1e00
	ds_read_b64_tr_b16 v[206:207], v145 offset:0x2600
	ds_read_b64_tr_b16 v[208:209], v145 offset:0x2e00
	ds_read_b64_tr_b16 v[228:229], v145 offset:0x3600
	ds_read_b64_tr_b16 v[230:231], v145 offset:0x3e00
	s_waitcnt lgkmcnt(8)
	v_mfma_f32_32x32x16_bf16 v[80:95], v[128:131], v[146:149], v[80:95]
	v_mfma_f32_32x32x16_bf16 v[80:95], v[132:135], v[150:153], v[80:95]
	v_mfma_f32_32x32x16_bf16 v[80:95], v[136:139], v[154:157], v[80:95]
	v_mfma_f32_32x32x16_bf16 v[80:95], v[140:143], v[194:197], v[80:95]
	ds_read_b64_tr_b16 v[146:147], v145 offset:0x4000
	ds_read_b64_tr_b16 v[148:149], v145 offset:0x4800
	ds_read_b64_tr_b16 v[150:151], v145 offset:0x5000
	ds_read_b64_tr_b16 v[152:153], v145 offset:0x5800
	ds_read_b64_tr_b16 v[154:155], v145 offset:0x6000
	ds_read_b64_tr_b16 v[156:157], v145 offset:0x6800
	ds_read_b64_tr_b16 v[194:195], v145 offset:0x7000
	ds_read_b64_tr_b16 v[196:197], v145 offset:0x7800
	s_waitcnt lgkmcnt(8)
	v_mfma_f32_32x32x16_bf16 v[64:79], v[128:131], v[198:201], v[64:79]
	v_mfma_f32_32x32x16_bf16 v[64:79], v[132:135], v[202:205], v[64:79]
	v_mfma_f32_32x32x16_bf16 v[64:79], v[136:139], v[206:209], v[64:79]
	v_mfma_f32_32x32x16_bf16 v[64:79], v[140:143], v[228:231], v[64:79]
	ds_read_b64_tr_b16 v[198:199], v145 offset:0x4200
	ds_read_b64_tr_b16 v[200:201], v145 offset:0x4a00
	ds_read_b64_tr_b16 v[202:203], v145 offset:0x5200
	ds_read_b64_tr_b16 v[204:205], v145 offset:0x5a00
	ds_read_b64_tr_b16 v[206:207], v145 offset:0x6200
	ds_read_b64_tr_b16 v[208:209], v145 offset:0x6a00
	ds_read_b64_tr_b16 v[228:229], v145 offset:0x7200
	ds_read_b64_tr_b16 v[230:231], v145 offset:0x7a00
	s_waitcnt lgkmcnt(8)
	v_mfma_f32_32x32x16_bf16 v[48:63], v[128:131], v[146:149], v[48:63]
	v_mfma_f32_32x32x16_bf16 v[48:63], v[132:135], v[150:153], v[48:63]
	v_mfma_f32_32x32x16_bf16 v[48:63], v[136:139], v[154:157], v[48:63]
	v_mfma_f32_32x32x16_bf16 v[48:63], v[140:143], v[194:197], v[48:63]
	ds_read_b64_tr_b16 v[146:147], v145 offset:0x4400
	ds_read_b64_tr_b16 v[148:149], v145 offset:0x4c00
	ds_read_b64_tr_b16 v[150:151], v145 offset:0x5400
	ds_read_b64_tr_b16 v[152:153], v145 offset:0x5c00
	ds_read_b64_tr_b16 v[154:155], v145 offset:0x6400
	ds_read_b64_tr_b16 v[156:157], v145 offset:0x6c00
	ds_read_b64_tr_b16 v[194:195], v145 offset:0x7400
	ds_read_b64_tr_b16 v[196:197], v145 offset:0x7c00
	s_waitcnt lgkmcnt(8)
	v_mfma_f32_32x32x16_bf16 v[32:47], v[128:131], v[198:201], v[32:47]
	v_mfma_f32_32x32x16_bf16 v[32:47], v[132:135], v[202:205], v[32:47]
	v_mfma_f32_32x32x16_bf16 v[32:47], v[136:139], v[206:209], v[32:47]
	v_mfma_f32_32x32x16_bf16 v[32:47], v[140:143], v[228:231], v[32:47]
	ds_read_b64_tr_b16 v[198:199], v145 offset:0x4600
	ds_read_b64_tr_b16 v[200:201], v145 offset:0x4e00
	ds_read_b64_tr_b16 v[202:203], v145 offset:0x5600
	ds_read_b64_tr_b16 v[204:205], v145 offset:0x5e00
	ds_read_b64_tr_b16 v[206:207], v145 offset:0x6600
	ds_read_b64_tr_b16 v[208:209], v145 offset:0x6e00
	ds_read_b64_tr_b16 v[228:229], v145 offset:0x7600
	ds_read_b64_tr_b16 v[230:231], v145 offset:0x7e00
	s_waitcnt lgkmcnt(8)
	v_mfma_f32_32x32x16_bf16 v[16:31], v[128:131], v[146:149], v[16:31]
	v_mfma_f32_32x32x16_bf16 v[16:31], v[132:135], v[150:153], v[16:31]
	v_mfma_f32_32x32x16_bf16 v[16:31], v[136:139], v[154:157], v[16:31]
	v_mfma_f32_32x32x16_bf16 v[16:31], v[140:143], v[194:197], v[16:31]
	s_waitcnt lgkmcnt(0)
	v_mfma_f32_32x32x16_bf16 v[0:15], v[128:131], v[198:201], v[0:15]
	v_mfma_f32_32x32x16_bf16 v[0:15], v[132:135], v[202:205], v[0:15]
	v_mfma_f32_32x32x16_bf16 v[0:15], v[136:139], v[206:209], v[0:15]
	v_mfma_f32_32x32x16_bf16 v[0:15], v[140:143], v[228:231], v[0:15]
	s_setprio 0
	s_add_i32 s8, s19, 0xc000
	s_cmp_lg_u32 s8, 0x24000
	s_cselect_b32 s8, s8, 0
	s_addk_i32 s2, 0x100
	s_waitcnt vmcnt(0) lgkmcnt(0)
	s_barrier
	s_add_u32 s16, s16, 0xc0000
	s_addc_u32 s17, s17, 0
	s_add_i32 s1, s1, 64
	s_cmp_eq_u32 s2, 0
	s_cbranch_scc0 .LBB0_126
